# DSA attention chunk restructured: fragments and bias lookups up front, score tiles interleaved, selects skipped for fully valid chunks, row-max DPP chains interleaved, paired bf16 convert; no op_sel o
# baseline (speedup 1.0000x reference)
.Lat_av_A:
	v_max_f32_e32 v2, v120, v121
	v_max_f32_e32 v3, v122, v123
	v_max_f32_e32 v158, v124, v125
	v_max_f32_e32 v159, v126, v127
	v_max_f32_dpp v2, v2, v2 quad_perm:[1,0,3,2] row_mask:0xf bank_mask:0xf bound_ctrl:1
	v_max_f32_dpp v3, v3, v3 quad_perm:[1,0,3,2] row_mask:0xf bank_mask:0xf bound_ctrl:1
	v_max_f32_dpp v158, v158, v158 quad_perm:[1,0,3,2] row_mask:0xf bank_mask:0xf bound_ctrl:1
	v_max_f32_dpp v159, v159, v159 quad_perm:[1,0,3,2] row_mask:0xf bank_mask:0xf bound_ctrl:1
	v_max_f32_dpp v2, v2, v2 quad_perm:[2,3,0,1] row_mask:0xf bank_mask:0xf bound_ctrl:1
	v_max_f32_dpp v3, v3, v3 quad_perm:[2,3,0,1] row_mask:0xf bank_mask:0xf bound_ctrl:1
	v_max_f32_dpp v158, v158, v158 quad_perm:[2,3,0,1] row_mask:0xf bank_mask:0xf bound_ctrl:1
	v_max_f32_dpp v159, v159, v159 quad_perm:[2,3,0,1] row_mask:0xf bank_mask:0xf bound_ctrl:1
	v_max_f32_dpp v2, v2, v2 row_half_mirror row_mask:0xf bank_mask:0xf bound_ctrl:1
	v_max_f32_dpp v3, v3, v3 row_half_mirror row_mask:0xf bank_mask:0xf bound_ctrl:1
	v_max_f32_dpp v158, v158, v158 row_half_mirror row_mask:0xf bank_mask:0xf bound_ctrl:1
	v_max_f32_dpp v159, v159, v159 row_half_mirror row_mask:0xf bank_mask:0xf bound_ctrl:1
	v_mov_b32_dpp v128, v2 row_mirror row_mask:0xf bank_mask:0xf bound_ctrl:1
	v_mov_b32_dpp v129, v3 row_mirror row_mask:0xf bank_mask:0xf bound_ctrl:1
	v_mov_b32_dpp v130, v158 row_mirror row_mask:0xf bank_mask:0xf bound_ctrl:1
	v_mov_b32_dpp v131, v159 row_mirror row_mask:0xf bank_mask:0xf bound_ctrl:1
	v_max3_f32 v239, v233, v2, v128
	v_max3_f32 v238, v232, v3, v129
	v_max3_f32 v151, v231, v158, v130
	v_max3_f32 v150, v230, v159, v131
	v_sub_f32_e32 v160, v233, v239
	v_sub_f32_e32 v161, v232, v238
	v_sub_f32_e32 v184, v231, v151
	v_sub_f32_e32 v185, v230, v150
	v_sub_f32_e32 v120, v120, v239
	v_sub_f32_e32 v121, v121, v239
	v_sub_f32_e32 v122, v122, v238
	v_sub_f32_e32 v123, v123, v238
	v_sub_f32_e32 v124, v124, v151
	v_sub_f32_e32 v125, v125, v151
	v_sub_f32_e32 v126, v126, v150
	v_sub_f32_e32 v127, v127, v150
	v_mov_b32_e32 v233, v239
	v_mov_b32_e32 v232, v238
	v_mov_b32_e32 v231, v151
	v_mov_b32_e32 v230, v150
	v_mul_f32_e32 v120, 0x3fb8aa3b, v120
	v_mul_f32_e32 v121, 0x3fb8aa3b, v121
	v_mul_f32_e32 v122, 0x3fb8aa3b, v122
	v_mul_f32_e32 v123, 0x3fb8aa3b, v123
	v_mul_f32_e32 v124, 0x3fb8aa3b, v124
	v_mul_f32_e32 v125, 0x3fb8aa3b, v125
	v_mul_f32_e32 v126, 0x3fb8aa3b, v126
	v_mul_f32_e32 v127, 0x3fb8aa3b, v127
	v_mul_f32_e32 v160, 0x3fb8aa3b, v160
	v_mul_f32_e32 v161, 0x3fb8aa3b, v161
	v_mul_f32_e32 v184, 0x3fb8aa3b, v184
	v_mul_f32_e32 v185, 0x3fb8aa3b, v185
	v_exp_f32_e32 v3, v120
	v_exp_f32_e32 v159, v121
	v_exp_f32_e32 v2, v122
	v_exp_f32_e32 v158, v123
	v_exp_f32_e32 v181, v124
	v_exp_f32_e32 v183, v125
	v_exp_f32_e32 v180, v126
	v_exp_f32_e32 v182, v127
	v_exp_f32_e32 v161, v161
	v_exp_f32_e32 v160, v160
	v_exp_f32_e32 v185, v185
	v_exp_f32_e32 v184, v184
	v_cvt_pk_bf16_f32 v128, v3, v159
	v_cvt_pk_bf16_f32 v129, v2, v158
	v_cvt_pk_bf16_f32 v130, v181, v183
	v_cvt_pk_bf16_f32 v131, v180, v182
	ds_write_b16 v221, v128 offset:8704
	ds_write_b16_d16_hi v221, v128 offset:8736
	ds_write_b16 v221, v129 offset:8784
	ds_write_b16_d16_hi v221, v129 offset:8816
	ds_write_b16 v221, v130 offset:8864
	ds_write_b16_d16_hi v221, v130 offset:8896
	ds_write_b16 v221, v131 offset:8944
	ds_write_b16_d16_hi v221, v131 offset:8976
	v_min3_f32 v0, v161, v160, v185
	v_min_f32_e32 v0, v0, v184
	s_waitcnt lgkmcnt(0)
	ds_read_b128 v[116:119], v222 offset:8704
	ds_read_b64_tr_b16 v[148:149], v193 offset:0
	ds_read_b64_tr_b16 v[150:151], v193 offset:1088
	ds_read_b64_tr_b16 v[144:145], v193 offset:32
	ds_read_b64_tr_b16 v[146:147], v193 offset:1120
	ds_read_b64_tr_b16 v[140:141], v193 offset:64
	ds_read_b64_tr_b16 v[142:143], v193 offset:1152
	ds_read_b64_tr_b16 v[136:137], v193 offset:96
	ds_read_b64_tr_b16 v[138:139], v193 offset:1184
	ds_read_b64_tr_b16 v[132:133], v193 offset:128
	ds_read_b64_tr_b16 v[134:135], v193 offset:1216
	ds_read_b64_tr_b16 v[128:129], v193 offset:160
	ds_read_b64_tr_b16 v[130:131], v193 offset:1248
	ds_read_b64_tr_b16 v[124:125], v193 offset:192
	ds_read_b64_tr_b16 v[126:127], v193 offset:1280
	ds_read_b64_tr_b16 v[120:121], v193 offset:224
	ds_read_b64_tr_b16 v[122:123], v193 offset:1312
	v_cmp_neq_f32_e32 vcc, 1.0, v0
	s_cbranch_vccz .Lat_nr_A
	v_pk_mul_f32 v[60:61], v[60:61], v[160:161]
	v_pk_mul_f32 v[62:63], v[62:63], v[184:185]
	v_pk_mul_f32 v[56:57], v[56:57], v[160:161]
	v_pk_mul_f32 v[58:59], v[58:59], v[184:185]
	v_pk_mul_f32 v[52:53], v[52:53], v[160:161]
	v_pk_mul_f32 v[54:55], v[54:55], v[184:185]
	v_pk_mul_f32 v[48:49], v[48:49], v[160:161]
	v_pk_mul_f32 v[50:51], v[50:51], v[184:185]
	v_pk_mul_f32 v[44:45], v[44:45], v[160:161]
	v_pk_mul_f32 v[46:47], v[46:47], v[184:185]
	v_pk_mul_f32 v[40:41], v[40:41], v[160:161]
	v_pk_mul_f32 v[42:43], v[42:43], v[184:185]
	v_pk_mul_f32 v[36:37], v[36:37], v[160:161]
	v_pk_mul_f32 v[38:39], v[38:39], v[184:185]
	v_pk_mul_f32 v[32:33], v[32:33], v[160:161]
	v_pk_mul_f32 v[34:35], v[34:35], v[184:185]
.Lat_nr_A:
	s_waitcnt lgkmcnt(0)
	v_mfma_f32_16x16x32_bf16 v[60:63], v[116:119], v[148:151], v[60:63]
	v_fma_f32 v2, v156, v161, v2
	v_fma_f32 v3, v157, v160, v3
	v_pk_add_f32 v[156:157], v[158:159], v[2:3]
	v_mfma_f32_16x16x32_bf16 v[56:59], v[116:119], v[144:147], v[56:59]
	v_fma_f32 v2, v154, v185, v180
	v_fma_f32 v3, v155, v184, v181
	v_pk_add_f32 v[154:155], v[182:183], v[2:3]
	s_add_i32 s6, s55, -2
	s_cmp_ge_i32 s6, s16
	v_mfma_f32_16x16x32_bf16 v[52:55], v[116:119], v[140:143], v[52:55]
	v_mfma_f32_16x16x32_bf16 v[48:51], v[116:119], v[136:139], v[48:51]
	v_mfma_f32_16x16x32_bf16 v[44:47], v[116:119], v[132:135], v[44:47]
	v_mfma_f32_16x16x32_bf16 v[40:43], v[116:119], v[128:131], v[40:43]
	v_mfma_f32_16x16x32_bf16 v[36:39], v[116:119], v[124:127], v[36:39]
	v_mfma_f32_16x16x32_bf16 v[32:35], v[116:119], v[120:123], v[32:35]
	s_cbranch_scc1 .LBB0_2524
	s_cmp_ge_i32 s55, s16
	ds_write_b128 v218, v[68:71]
	ds_write_b128 v218, v[76:79] offset:1088
	ds_write_b128 v218, v[84:87] offset:2176
	ds_write_b128 v218, v[92:95] offset:3264
	ds_write_b128 v218, v[100:103] offset:4352
	ds_write_b128 v218, v[104:107] offset:5440
	ds_write_b128 v218, v[108:111] offset:6528
	ds_write_b128 v218, v[112:115] offset:7616
	s_cbranch_scc1 .LBB0_2573
	v_add_u32_e32 v114, s57, v212
	v_add_u32_e32 v114, 0x20180, v114
	ds_read_b32 v68, v114
	ds_read_b32 v76, v114 offset:16
	ds_read_b32 v84, v114 offset:32
	ds_read_b32 v92, v114 offset:48
	ds_read_b32 v100, v114 offset:64
	ds_read_b32 v104, v114 offset:80
	ds_read_b32 v108, v114 offset:96
	ds_read_b32 v112, v114 offset:112
	s_waitcnt lgkmcnt(0)
	v_lshl_or_b32 v68, v68, 8, v152
	global_load_dwordx4 v[68:71], v68, s[96:97]
	v_lshl_or_b32 v76, v76, 8, v152
	global_load_dwordx4 v[76:79], v76, s[96:97]
	v_lshl_or_b32 v84, v84, 8, v152
	global_load_dwordx4 v[84:87], v84, s[96:97]
	v_lshl_or_b32 v92, v92, 8, v152
	global_load_dwordx4 v[92:95], v92, s[96:97]
	v_lshl_or_b32 v100, v100, 8, v152
	global_load_dwordx4 v[100:103], v100, s[96:97]
	v_lshl_or_b32 v104, v104, 8, v152
	global_load_dwordx4 v[104:107], v104, s[96:97]
	v_lshl_or_b32 v108, v108, 8, v152
	global_load_dwordx4 v[108:111], v108, s[96:97]
	v_lshl_or_b32 v112, v112, 8, v152
	global_load_dwordx4 v[112:115], v112, s[96:97]

.Lat_nr_B:
	s_waitcnt lgkmcnt(0)
	v_mfma_f32_16x16x32_bf16 v[60:63], v[116:119], v[148:151], v[60:63]
	v_fma_f32 v2, v156, v161, v2
	v_fma_f32 v3, v157, v160, v3
	v_pk_add_f32 v[156:157], v[158:159], v[2:3]
	v_mfma_f32_16x16x32_bf16 v[56:59], v[116:119], v[144:147], v[56:59]
	v_fma_f32 v2, v154, v185, v180
	v_fma_f32 v3, v155, v184, v181
	v_pk_add_f32 v[154:155], v[182:183], v[2:3]
	v_mfma_f32_16x16x32_bf16 v[52:55], v[116:119], v[140:143], v[52:55]
	v_mfma_f32_16x16x32_bf16 v[48:51], v[116:119], v[136:139], v[48:51]
	v_mfma_f32_16x16x32_bf16 v[44:47], v[116:119], v[132:135], v[44:47]
	v_mfma_f32_16x16x32_bf16 v[40:43], v[116:119], v[128:131], v[40:43]
	v_mfma_f32_16x16x32_bf16 v[36:39], v[116:119], v[124:127], v[36:39]
	v_mfma_f32_16x16x32_bf16 v[32:35], v[116:119], v[120:123], v[32:35]
	s_branch .LBB0_2525
